# as best, minus the redundant wave-half test in the waves-0-3 fast path (D loops)
# speedup vs baseline: 1.0038x; 1.0029x over previous
; #define SBAR() __builtin_amdgcn_sched_barrier(0)
; template <int D0> __device__ __forceinline__ void pv_one(f32x16& od, int vb, bf16x8 pa0, bf16x8 pa1, bf16x8 pa2, bf16x8 pa3) {
;     const s16x4 l0 = tr_read<v_rd_off(D0, 0, 0)>(vb), h0 = tr_read<v_rd_off(D0, 0, 1)>(vb), l1 = tr_read<v_rd_off(D0, 1, 0)>(vb), h1 = tr_read<v_rd_off(D0, 1, 1)>(vb);
;     const s16x4 l2 = tr_read<v_rd_off(D0, 2, 0)>(vb), h2 = tr_read<v_rd_off(D0, 2, 1)>(vb), l3 = tr_read<v_rd_off(D0, 3, 0)>(vb), h3 = tr_read<v_rd_off(D0, 3, 1)>(vb);
;     asm volatile("s_waitcnt lgkmcnt(0)" ::: "memory"); SBAR();
;     ...
;     od = __builtin_amdgcn_mfma_f32_32x32x16_bf16(pa0, PK(l0, h0), od, 0, 0, 0);
;     od = __builtin_amdgcn_mfma_f32_32x32x16_bf16(pa1, PK(l1, h1), od, 0, 0, 0);
;     od = __builtin_amdgcn_mfma_f32_32x32x16_bf16(pa2, PK(l2, h2), od, 0, 0, 0);
;     od = __builtin_amdgcn_mfma_f32_32x32x16_bf16(pa3, PK(l3, h3), od, 0, 0, 0);
;     ...
; }
; template <bool RSM> __device__ __forceinline__ void pv_d0(f32x16* o, f32x16& lacc, int vb, bf16x8 pa0, bf16x8 pa1, bf16x8 pa2, bf16x8 pa3) {
;     if (RSM) {
;         const bf16x8 ones = {0x3F80, 0x3F80, 0x3F80, 0x3F80, 0x3F80, 0x3F80, 0x3F80, 0x3F80};
;         lacc = __builtin_amdgcn_mfma_f32_32x32x16_bf16(pa0, ones, lacc, 0, 0, 0);
;         lacc = __builtin_amdgcn_mfma_f32_32x32x16_bf16(pa1, ones, lacc, 0, 0, 0);
;         lacc = __builtin_amdgcn_mfma_f32_32x32x16_bf16(pa2, ones, lacc, 0, 0, 0);
;         lacc = __builtin_amdgcn_mfma_f32_32x32x16_bf16(pa3, ones, lacc, 0, 0, 0); }
;     pv_one<0>(o[0], vb, pa0, pa1, pa2, pa3); pv_one<1>(o[1], vb, pa0, pa1, pa2, pa3); pv_one<2>(o[2], vb, pa0, pa1, pa2, pa3); pv_one<3>(o[3], vb, pa0, pa1, pa2, pa3);
; }
.LBB0_704:
	s_mov_b32 s38, s36
	s_mov_b32 s39, s36
	s_mov_b32 s37, s36
	v_mov_b64_e32 v[134:135], s[38:39]
	v_mov_b64_e32 v[132:133], s[36:37]
	s_lshl_b32 s23, s35, 14
	v_add_u32_e32 v0, s23, v230
	v_mfma_f32_32x32x16_bf16 v[96:111], v[6:9], v[132:135], v[96:111]
	ds_read_b64_tr_b16 v[136:137], v0 offset:0
	ds_read_b64_tr_b16 v[138:139], v0 offset:0x800
	ds_read_b64_tr_b16 v[140:141], v0 offset:0x1000
	ds_read_b64_tr_b16 v[142:143], v0 offset:0x1800
	ds_read_b64_tr_b16 v[192:193], v0 offset:0x2000
	ds_read_b64_tr_b16 v[194:195], v0 offset:0x2800
	ds_read_b64_tr_b16 v[196:197], v0 offset:0x3000
	v_mfma_f32_32x32x16_bf16 v[96:111], v[2:5], v[132:135], v[96:111]
	ds_read_b64_tr_b16 v[198:199], v0 offset:0x3800
	s_waitcnt lgkmcnt(0)
	v_mfma_f32_32x32x16_bf16 v[96:111], v[128:131], v[132:135], v[96:111]
	v_mfma_f32_32x32x16_bf16 v[96:111], v[10:13], v[132:135], v[96:111]
	v_mfma_f32_32x32x16_bf16 v[80:95], v[6:9], v[136:139], v[80:95]
	ds_read_b64_tr_b16 v[132:133], v0 offset:0x200
	ds_read_b64_tr_b16 v[134:135], v0 offset:0xa00
	ds_read_b64_tr_b16 v[136:137], v0 offset:0x1200
	ds_read_b64_tr_b16 v[138:139], v0 offset:0x1a00
	v_mfma_f32_32x32x16_bf16 v[80:95], v[2:5], v[140:143], v[80:95]
	ds_read_b64_tr_b16 v[140:141], v0 offset:0x2200
	ds_read_b64_tr_b16 v[142:143], v0 offset:0x2a00
	v_mfma_f32_32x32x16_bf16 v[80:95], v[128:131], v[192:195], v[80:95]
	ds_read_b64_tr_b16 v[192:193], v0 offset:0x3200
	ds_read_b64_tr_b16 v[194:195], v0 offset:0x3a00
	s_waitcnt lgkmcnt(0)
	v_mfma_f32_32x32x16_bf16 v[80:95], v[10:13], v[196:199], v[80:95]
	v_mfma_f32_32x32x16_bf16 v[64:79], v[6:9], v[132:135], v[64:79]
	ds_read_b64_tr_b16 v[132:133], v0 offset:0x400
	ds_read_b64_tr_b16 v[134:135], v0 offset:0xc00
	v_mfma_f32_32x32x16_bf16 v[64:79], v[2:5], v[136:139], v[64:79]
	ds_read_b64_tr_b16 v[136:137], v0 offset:0x1400
	ds_read_b64_tr_b16 v[138:139], v0 offset:0x1c00
	v_mfma_f32_32x32x16_bf16 v[64:79], v[128:131], v[140:143], v[64:79]
	ds_read_b64_tr_b16 v[140:141], v0 offset:0x2400
	ds_read_b64_tr_b16 v[142:143], v0 offset:0x2c00
	v_mfma_f32_32x32x16_bf16 v[64:79], v[10:13], v[192:195], v[64:79]
	ds_read_b64_tr_b16 v[192:193], v0 offset:0x3400
	ds_read_b64_tr_b16 v[194:195], v0 offset:0x3c00
	s_waitcnt lgkmcnt(0)
	v_mfma_f32_32x32x16_bf16 v[48:63], v[6:9], v[132:135], v[48:63]
	ds_read_b64_tr_b16 v[132:133], v0 offset:0x600
	ds_read_b64_tr_b16 v[134:135], v0 offset:0xe00
	v_mfma_f32_32x32x16_bf16 v[48:63], v[2:5], v[136:139], v[48:63]
	ds_read_b64_tr_b16 v[136:137], v0 offset:0x1600
	ds_read_b64_tr_b16 v[138:139], v0 offset:0x1e00
	v_mfma_f32_32x32x16_bf16 v[48:63], v[128:131], v[140:143], v[48:63]
	ds_read_b64_tr_b16 v[140:141], v0 offset:0x2600
	ds_read_b64_tr_b16 v[142:143], v0 offset:0x2e00
	v_mfma_f32_32x32x16_bf16 v[48:63], v[10:13], v[192:195], v[48:63]
	ds_read_b64_tr_b16 v[192:193], v0 offset:0x3600
	ds_read_b64_tr_b16 v[194:195], v0 offset:0x3e00
	s_waitcnt lgkmcnt(0)
	s_cmpk_gt_u32 s57, 0xfc
	s_cbranch_scc1 .Lmy_slow_0
	s_mov_b64 s[20:21], -1
	s_add_i32 m0, s81, s22
	s_addk_i32 s23, 0xc000
	s_cmp_gt_i32 s35, 0
	s_cselect_b32 s20, s23, 0xc000
	s_waitcnt vmcnt(3) lgkmcnt(0)
	s_barrier
	v_mfma_f32_32x32x16_bf16 v[32:47], v[6:9], v[132:135], v[32:47]
	s_and_b64 vcc, exec, s[0:1]
	v_mfma_f32_32x32x16_bf16 v[32:47], v[2:5], v[136:139], v[32:47]
	v_mfma_f32_32x32x16_bf16 v[32:47], v[128:131], v[140:143], v[32:47]
	v_mfma_f32_32x32x16_bf16 v[32:47], v[10:13], v[192:195], v[32:47]
	s_add_i32 s20, s63, s20
	global_load_lds_dwordx4 v[214:215], off
	s_mov_b32 m0, s20
	v_lshl_add_u64 v[214:215], v[214:215], 0, s[74:75]
	global_load_lds_dwordx4 v[212:213], off
	s_add_i32 m0, s20, 0x2000
	v_lshl_add_u64 v[2:3], v[212:213], 0, s[74:75]
	global_load_lds_dwordx4 v[216:217], off
	v_lshl_add_u64 v[4:5], v[216:217], 0, s[74:75]
	v_mov_b64_e32 v[216:217], v[4:5]
	v_mov_b64_e32 v[212:213], v[2:3]
	s_branch .LBB0_709

; #define SBAR() __builtin_amdgcn_sched_barrier(0)
; template <int D0> __device__ __forceinline__ void pv_one(f32x16& od, int vb, bf16x8 pa0, bf16x8 pa1, bf16x8 pa2, bf16x8 pa3) {
;     const s16x4 l0 = tr_read<v_rd_off(D0, 0, 0)>(vb), h0 = tr_read<v_rd_off(D0, 0, 1)>(vb), l1 = tr_read<v_rd_off(D0, 1, 0)>(vb), h1 = tr_read<v_rd_off(D0, 1, 1)>(vb);
;     const s16x4 l2 = tr_read<v_rd_off(D0, 2, 0)>(vb), h2 = tr_read<v_rd_off(D0, 2, 1)>(vb), l3 = tr_read<v_rd_off(D0, 3, 0)>(vb), h3 = tr_read<v_rd_off(D0, 3, 1)>(vb);
;     asm volatile("s_waitcnt lgkmcnt(0)" ::: "memory"); SBAR();
;     ...
;     od = __builtin_amdgcn_mfma_f32_32x32x16_bf16(pa0, PK(l0, h0), od, 0, 0, 0);
;     od = __builtin_amdgcn_mfma_f32_32x32x16_bf16(pa1, PK(l1, h1), od, 0, 0, 0);
;     od = __builtin_amdgcn_mfma_f32_32x32x16_bf16(pa2, PK(l2, h2), od, 0, 0, 0);
;     od = __builtin_amdgcn_mfma_f32_32x32x16_bf16(pa3, PK(l3, h3), od, 0, 0, 0);
;     ...
; }
; template <bool RSM> __device__ __forceinline__ void pv_d0(f32x16* o, f32x16& lacc, int vb, bf16x8 pa0, bf16x8 pa1, bf16x8 pa2, bf16x8 pa3) {
;     if (RSM) {
;         const bf16x8 ones = {0x3F80, 0x3F80, 0x3F80, 0x3F80, 0x3F80, 0x3F80, 0x3F80, 0x3F80};
;         lacc = __builtin_amdgcn_mfma_f32_32x32x16_bf16(pa0, ones, lacc, 0, 0, 0);
;         lacc = __builtin_amdgcn_mfma_f32_32x32x16_bf16(pa1, ones, lacc, 0, 0, 0);
;         lacc = __builtin_amdgcn_mfma_f32_32x32x16_bf16(pa2, ones, lacc, 0, 0, 0);
;         lacc = __builtin_amdgcn_mfma_f32_32x32x16_bf16(pa3, ones, lacc, 0, 0, 0); }
;     pv_one<0>(o[0], vb, pa0, pa1, pa2, pa3); pv_one<1>(o[1], vb, pa0, pa1, pa2, pa3); pv_one<2>(o[2], vb, pa0, pa1, pa2, pa3); pv_one<3>(o[3], vb, pa0, pa1, pa2, pa3);
; }
.LBB0_719:
	s_mov_b32 s38, s36
	s_mov_b32 s39, s36
	s_mov_b32 s37, s36
	v_mov_b64_e32 v[150:151], s[38:39]
	v_mov_b64_e32 v[148:149], s[36:37]
	s_lshl_b32 s37, s35, 14
	v_add_u32_e32 v14, s37, v230
	v_mfma_f32_32x32x16_bf16 v[96:111], v[6:9], v[148:151], v[96:111]
	ds_read_b64_tr_b16 v[152:153], v14 offset:0
	ds_read_b64_tr_b16 v[154:155], v14 offset:0x800
	ds_read_b64_tr_b16 v[156:157], v14 offset:0x1000
	ds_read_b64_tr_b16 v[158:159], v14 offset:0x1800
	ds_read_b64_tr_b16 v[192:193], v14 offset:0x2000
	ds_read_b64_tr_b16 v[194:195], v14 offset:0x2800
	ds_read_b64_tr_b16 v[196:197], v14 offset:0x3000
	v_mfma_f32_32x32x16_bf16 v[96:111], v[2:5], v[148:151], v[96:111]
	ds_read_b64_tr_b16 v[198:199], v14 offset:0x3800
	s_waitcnt lgkmcnt(0)
	v_mfma_f32_32x32x16_bf16 v[96:111], v[144:147], v[148:151], v[96:111]
	v_mfma_f32_32x32x16_bf16 v[96:111], v[10:13], v[148:151], v[96:111]
	v_mfma_f32_32x32x16_bf16 v[80:95], v[6:9], v[152:155], v[80:95]
	ds_read_b64_tr_b16 v[148:149], v14 offset:0x200
	ds_read_b64_tr_b16 v[150:151], v14 offset:0xa00
	ds_read_b64_tr_b16 v[152:153], v14 offset:0x1200
	ds_read_b64_tr_b16 v[154:155], v14 offset:0x1a00
	v_mfma_f32_32x32x16_bf16 v[80:95], v[2:5], v[156:159], v[80:95]
	ds_read_b64_tr_b16 v[156:157], v14 offset:0x2200
	ds_read_b64_tr_b16 v[158:159], v14 offset:0x2a00
	v_mfma_f32_32x32x16_bf16 v[80:95], v[144:147], v[192:195], v[80:95]
	ds_read_b64_tr_b16 v[192:193], v14 offset:0x3200
	ds_read_b64_tr_b16 v[194:195], v14 offset:0x3a00
	s_waitcnt lgkmcnt(0)
	v_mfma_f32_32x32x16_bf16 v[80:95], v[10:13], v[196:199], v[80:95]
	v_mfma_f32_32x32x16_bf16 v[64:79], v[6:9], v[148:151], v[64:79]
	ds_read_b64_tr_b16 v[148:149], v14 offset:0x400
	ds_read_b64_tr_b16 v[150:151], v14 offset:0xc00
	v_mfma_f32_32x32x16_bf16 v[64:79], v[2:5], v[152:155], v[64:79]
	ds_read_b64_tr_b16 v[152:153], v14 offset:0x1400
	ds_read_b64_tr_b16 v[154:155], v14 offset:0x1c00
	v_mfma_f32_32x32x16_bf16 v[64:79], v[144:147], v[156:159], v[64:79]
	ds_read_b64_tr_b16 v[156:157], v14 offset:0x2400
	ds_read_b64_tr_b16 v[158:159], v14 offset:0x2c00
	v_mfma_f32_32x32x16_bf16 v[64:79], v[10:13], v[192:195], v[64:79]
	ds_read_b64_tr_b16 v[192:193], v14 offset:0x3400
	ds_read_b64_tr_b16 v[194:195], v14 offset:0x3c00
	s_waitcnt lgkmcnt(0)
	v_mfma_f32_32x32x16_bf16 v[48:63], v[6:9], v[148:151], v[48:63]
	ds_read_b64_tr_b16 v[148:149], v14 offset:0x600
	ds_read_b64_tr_b16 v[150:151], v14 offset:0xe00
	v_mfma_f32_32x32x16_bf16 v[48:63], v[2:5], v[152:155], v[48:63]
	ds_read_b64_tr_b16 v[152:153], v14 offset:0x1600
	ds_read_b64_tr_b16 v[154:155], v14 offset:0x1e00
	v_mfma_f32_32x32x16_bf16 v[48:63], v[144:147], v[156:159], v[48:63]
	ds_read_b64_tr_b16 v[156:157], v14 offset:0x2600
	ds_read_b64_tr_b16 v[158:159], v14 offset:0x2e00
	v_mfma_f32_32x32x16_bf16 v[48:63], v[10:13], v[192:195], v[48:63]
	ds_read_b64_tr_b16 v[192:193], v14 offset:0x3600
	ds_read_b64_tr_b16 v[194:195], v14 offset:0x3e00
	s_waitcnt lgkmcnt(0)
	s_cmpk_gt_u32 s57, 0xfb
	s_cbranch_scc1 .Lmy_slow_1
	s_mov_b64 s[22:23], -1
	s_add_i32 m0, s81, s78
	s_addk_i32 s37, 0xc000
	s_cmp_gt_i32 s35, 0
	s_cselect_b32 s22, s37, 0xc000
	s_waitcnt vmcnt(3) lgkmcnt(0)
	s_barrier
	v_mfma_f32_32x32x16_bf16 v[32:47], v[6:9], v[148:151], v[32:47]
	s_and_b64 vcc, exec, s[0:1]
	v_mfma_f32_32x32x16_bf16 v[32:47], v[2:5], v[152:155], v[32:47]
	v_mfma_f32_32x32x16_bf16 v[32:47], v[144:147], v[156:159], v[32:47]
	v_mfma_f32_32x32x16_bf16 v[32:47], v[10:13], v[192:195], v[32:47]
	s_add_i32 s22, s63, s22
	global_load_lds_dwordx4 v[214:215], off
	s_mov_b32 m0, s22
	v_lshl_add_u64 v[214:215], v[214:215], 0, s[74:75]
	global_load_lds_dwordx4 v[212:213], off
	s_add_i32 m0, s22, 0x2000
	v_lshl_add_u64 v[2:3], v[212:213], 0, s[74:75]
	global_load_lds_dwordx4 v[216:217], off
	v_lshl_add_u64 v[4:5], v[216:217], 0, s[74:75]
	v_mov_b64_e32 v[216:217], v[4:5]
	v_mov_b64_e32 v[212:213], v[2:3]
	s_branch .LBB0_724

; #define SBAR() __builtin_amdgcn_sched_barrier(0)
; template <int D0> __device__ __forceinline__ void pv_one(f32x16& od, int vb, bf16x8 pa0, bf16x8 pa1, bf16x8 pa2, bf16x8 pa3) {
;     const s16x4 l0 = tr_read<v_rd_off(D0, 0, 0)>(vb), h0 = tr_read<v_rd_off(D0, 0, 1)>(vb), l1 = tr_read<v_rd_off(D0, 1, 0)>(vb), h1 = tr_read<v_rd_off(D0, 1, 1)>(vb);
;     const s16x4 l2 = tr_read<v_rd_off(D0, 2, 0)>(vb), h2 = tr_read<v_rd_off(D0, 2, 1)>(vb), l3 = tr_read<v_rd_off(D0, 3, 0)>(vb), h3 = tr_read<v_rd_off(D0, 3, 1)>(vb);
;     asm volatile("s_waitcnt lgkmcnt(0)" ::: "memory"); SBAR();
;     ...
;     od = __builtin_amdgcn_mfma_f32_32x32x16_bf16(pa0, PK(l0, h0), od, 0, 0, 0);
;     od = __builtin_amdgcn_mfma_f32_32x32x16_bf16(pa1, PK(l1, h1), od, 0, 0, 0);
;     od = __builtin_amdgcn_mfma_f32_32x32x16_bf16(pa2, PK(l2, h2), od, 0, 0, 0);
;     od = __builtin_amdgcn_mfma_f32_32x32x16_bf16(pa3, PK(l3, h3), od, 0, 0, 0);
;     ...
; }
; template <bool RSM> __device__ __forceinline__ void pv_d0(f32x16* o, f32x16& lacc, int vb, bf16x8 pa0, bf16x8 pa1, bf16x8 pa2, bf16x8 pa3) {
;     if (RSM) {
;         const bf16x8 ones = {0x3F80, 0x3F80, 0x3F80, 0x3F80, 0x3F80, 0x3F80, 0x3F80, 0x3F80};
;         lacc = __builtin_amdgcn_mfma_f32_32x32x16_bf16(pa0, ones, lacc, 0, 0, 0);
;         lacc = __builtin_amdgcn_mfma_f32_32x32x16_bf16(pa1, ones, lacc, 0, 0, 0);
;         lacc = __builtin_amdgcn_mfma_f32_32x32x16_bf16(pa2, ones, lacc, 0, 0, 0);
;         lacc = __builtin_amdgcn_mfma_f32_32x32x16_bf16(pa3, ones, lacc, 0, 0, 0); }
;     pv_one<0>(o[0], vb, pa0, pa1, pa2, pa3); pv_one<1>(o[1], vb, pa0, pa1, pa2, pa3); pv_one<2>(o[2], vb, pa0, pa1, pa2, pa3); pv_one<3>(o[3], vb, pa0, pa1, pa2, pa3);
; }
.LBB0_779:
	s_mov_b32 s38, s36
	s_mov_b32 s39, s36
	s_mov_b32 s37, s36
	v_mov_b64_e32 v[118:119], s[38:39]
	v_mov_b64_e32 v[116:117], s[36:37]
	s_lshl_b32 s15, s18, 14
	v_add_u32_e32 v0, s15, v192
	v_mfma_f32_32x32x16_bf16 v[80:95], v[6:9], v[116:119], v[80:95]
	ds_read_b64_tr_b16 v[120:121], v0 offset:0
	ds_read_b64_tr_b16 v[122:123], v0 offset:0x800
	ds_read_b64_tr_b16 v[124:125], v0 offset:0x1000
	ds_read_b64_tr_b16 v[126:127], v0 offset:0x1800
	ds_read_b64_tr_b16 v[176:177], v0 offset:0x2000
	ds_read_b64_tr_b16 v[178:179], v0 offset:0x2800
	ds_read_b64_tr_b16 v[180:181], v0 offset:0x3000
	v_mfma_f32_32x32x16_bf16 v[80:95], v[2:5], v[116:119], v[80:95]
	ds_read_b64_tr_b16 v[182:183], v0 offset:0x3800
	s_waitcnt lgkmcnt(0)
	v_mfma_f32_32x32x16_bf16 v[80:95], v[112:115], v[116:119], v[80:95]
	v_mfma_f32_32x32x16_bf16 v[80:95], v[10:13], v[116:119], v[80:95]
	v_mfma_f32_32x32x16_bf16 v[64:79], v[6:9], v[120:123], v[64:79]
	ds_read_b64_tr_b16 v[116:117], v0 offset:0x200
	ds_read_b64_tr_b16 v[118:119], v0 offset:0xa00
	ds_read_b64_tr_b16 v[120:121], v0 offset:0x1200
	ds_read_b64_tr_b16 v[122:123], v0 offset:0x1a00
	v_mfma_f32_32x32x16_bf16 v[64:79], v[2:5], v[124:127], v[64:79]
	ds_read_b64_tr_b16 v[124:125], v0 offset:0x2200
	ds_read_b64_tr_b16 v[126:127], v0 offset:0x2a00
	v_mfma_f32_32x32x16_bf16 v[64:79], v[112:115], v[176:179], v[64:79]
	ds_read_b64_tr_b16 v[176:177], v0 offset:0x3200
	ds_read_b64_tr_b16 v[178:179], v0 offset:0x3a00
	s_waitcnt lgkmcnt(0)
	v_mfma_f32_32x32x16_bf16 v[64:79], v[10:13], v[180:183], v[64:79]
	v_mfma_f32_32x32x16_bf16 v[48:63], v[6:9], v[116:119], v[48:63]
	ds_read_b64_tr_b16 v[116:117], v0 offset:0x400
	ds_read_b64_tr_b16 v[118:119], v0 offset:0xc00
	v_mfma_f32_32x32x16_bf16 v[48:63], v[2:5], v[120:123], v[48:63]
	ds_read_b64_tr_b16 v[120:121], v0 offset:0x1400
	ds_read_b64_tr_b16 v[122:123], v0 offset:0x1c00
	v_mfma_f32_32x32x16_bf16 v[48:63], v[112:115], v[124:127], v[48:63]
	ds_read_b64_tr_b16 v[124:125], v0 offset:0x2400
	ds_read_b64_tr_b16 v[126:127], v0 offset:0x2c00
	v_mfma_f32_32x32x16_bf16 v[48:63], v[10:13], v[176:179], v[48:63]
	ds_read_b64_tr_b16 v[176:177], v0 offset:0x3400
	ds_read_b64_tr_b16 v[178:179], v0 offset:0x3c00
	s_waitcnt lgkmcnt(0)
	v_mfma_f32_32x32x16_bf16 v[32:47], v[6:9], v[116:119], v[32:47]
	ds_read_b64_tr_b16 v[116:117], v0 offset:0x600
	ds_read_b64_tr_b16 v[118:119], v0 offset:0xe00
	v_mfma_f32_32x32x16_bf16 v[32:47], v[2:5], v[120:123], v[32:47]
	ds_read_b64_tr_b16 v[120:121], v0 offset:0x1600
	ds_read_b64_tr_b16 v[122:123], v0 offset:0x1e00
	v_mfma_f32_32x32x16_bf16 v[32:47], v[112:115], v[124:127], v[32:47]
	ds_read_b64_tr_b16 v[124:125], v0 offset:0x2600
	ds_read_b64_tr_b16 v[126:127], v0 offset:0x2e00
	v_mfma_f32_32x32x16_bf16 v[32:47], v[10:13], v[176:179], v[32:47]
	ds_read_b64_tr_b16 v[176:177], v0 offset:0x3600
	ds_read_b64_tr_b16 v[178:179], v0 offset:0x3e00
	s_waitcnt lgkmcnt(0)
	s_cmpk_gt_u32 s17, 0xfc
	s_cbranch_scc1 .Lmy_slow_2
	s_mov_b64 s[12:13], -1
	s_add_i32 m0, s81, s14
	s_addk_i32 s15, 0xc000
	s_cmp_gt_i32 s18, 0
	s_cselect_b32 s12, s15, 0xc000
	s_waitcnt vmcnt(3) lgkmcnt(0)
	s_barrier
	v_mfma_f32_32x32x16_bf16 v[16:31], v[6:9], v[116:119], v[16:31]
	s_and_b64 vcc, exec, s[0:1]
	v_mfma_f32_32x32x16_bf16 v[16:31], v[2:5], v[120:123], v[16:31]
	v_mfma_f32_32x32x16_bf16 v[16:31], v[112:115], v[124:127], v[16:31]
	v_mfma_f32_32x32x16_bf16 v[16:31], v[10:13], v[176:179], v[16:31]
	s_add_i32 s12, s63, s12
	global_load_lds_dwordx4 v[184:185], off
	s_mov_b32 m0, s12
	v_lshl_add_u64 v[184:185], v[184:185], 0, s[74:75]
	global_load_lds_dwordx4 v[186:187], off
	s_add_i32 m0, s12, 0x2000
	v_lshl_add_u64 v[2:3], v[186:187], 0, s[74:75]
	global_load_lds_dwordx4 v[188:189], off
	v_lshl_add_u64 v[4:5], v[188:189], 0, s[74:75]
	v_mov_b64_e32 v[188:189], v[4:5]
	v_mov_b64_e32 v[186:187], v[2:3]
	s_branch .LBB0_784

; #define SBAR() __builtin_amdgcn_sched_barrier(0)
; template <int D0> __device__ __forceinline__ void pv_one(f32x16& od, int vb, bf16x8 pa0, bf16x8 pa1, bf16x8 pa2, bf16x8 pa3) {
;     const s16x4 l0 = tr_read<v_rd_off(D0, 0, 0)>(vb), h0 = tr_read<v_rd_off(D0, 0, 1)>(vb), l1 = tr_read<v_rd_off(D0, 1, 0)>(vb), h1 = tr_read<v_rd_off(D0, 1, 1)>(vb);
;     const s16x4 l2 = tr_read<v_rd_off(D0, 2, 0)>(vb), h2 = tr_read<v_rd_off(D0, 2, 1)>(vb), l3 = tr_read<v_rd_off(D0, 3, 0)>(vb), h3 = tr_read<v_rd_off(D0, 3, 1)>(vb);
;     asm volatile("s_waitcnt lgkmcnt(0)" ::: "memory"); SBAR();
;     ...
;     od = __builtin_amdgcn_mfma_f32_32x32x16_bf16(pa0, PK(l0, h0), od, 0, 0, 0);
;     od = __builtin_amdgcn_mfma_f32_32x32x16_bf16(pa1, PK(l1, h1), od, 0, 0, 0);
;     od = __builtin_amdgcn_mfma_f32_32x32x16_bf16(pa2, PK(l2, h2), od, 0, 0, 0);
;     od = __builtin_amdgcn_mfma_f32_32x32x16_bf16(pa3, PK(l3, h3), od, 0, 0, 0);
;     ...
; }
; template <bool RSM> __device__ __forceinline__ void pv_d0(f32x16* o, f32x16& lacc, int vb, bf16x8 pa0, bf16x8 pa1, bf16x8 pa2, bf16x8 pa3) {
;     if (RSM) {
;         const bf16x8 ones = {0x3F80, 0x3F80, 0x3F80, 0x3F80, 0x3F80, 0x3F80, 0x3F80, 0x3F80};
;         lacc = __builtin_amdgcn_mfma_f32_32x32x16_bf16(pa0, ones, lacc, 0, 0, 0);
;         lacc = __builtin_amdgcn_mfma_f32_32x32x16_bf16(pa1, ones, lacc, 0, 0, 0);
;         lacc = __builtin_amdgcn_mfma_f32_32x32x16_bf16(pa2, ones, lacc, 0, 0, 0);
;         lacc = __builtin_amdgcn_mfma_f32_32x32x16_bf16(pa3, ones, lacc, 0, 0, 0); }
;     pv_one<0>(o[0], vb, pa0, pa1, pa2, pa3); pv_one<1>(o[1], vb, pa0, pa1, pa2, pa3); pv_one<2>(o[2], vb, pa0, pa1, pa2, pa3); pv_one<3>(o[3], vb, pa0, pa1, pa2, pa3);
; }
.LBB0_794:
	s_mov_b32 s38, s36
	s_mov_b32 s39, s36
	s_mov_b32 s37, s36
	v_mov_b64_e32 v[134:135], s[38:39]
	v_mov_b64_e32 v[132:133], s[36:37]
	s_lshl_b32 s31, s18, 14
	v_add_u32_e32 v14, s31, v192
	v_mfma_f32_32x32x16_bf16 v[80:95], v[6:9], v[132:135], v[80:95]
	ds_read_b64_tr_b16 v[136:137], v14 offset:0
	ds_read_b64_tr_b16 v[138:139], v14 offset:0x800
	ds_read_b64_tr_b16 v[140:141], v14 offset:0x1000
	ds_read_b64_tr_b16 v[142:143], v14 offset:0x1800
	ds_read_b64_tr_b16 v[176:177], v14 offset:0x2000
	ds_read_b64_tr_b16 v[178:179], v14 offset:0x2800
	ds_read_b64_tr_b16 v[180:181], v14 offset:0x3000
	v_mfma_f32_32x32x16_bf16 v[80:95], v[2:5], v[132:135], v[80:95]
	ds_read_b64_tr_b16 v[182:183], v14 offset:0x3800
	s_waitcnt lgkmcnt(0)
	v_mfma_f32_32x32x16_bf16 v[80:95], v[128:131], v[132:135], v[80:95]
	v_mfma_f32_32x32x16_bf16 v[80:95], v[10:13], v[132:135], v[80:95]
	v_mfma_f32_32x32x16_bf16 v[64:79], v[6:9], v[136:139], v[64:79]
	ds_read_b64_tr_b16 v[132:133], v14 offset:0x200
	ds_read_b64_tr_b16 v[134:135], v14 offset:0xa00
	ds_read_b64_tr_b16 v[136:137], v14 offset:0x1200
	ds_read_b64_tr_b16 v[138:139], v14 offset:0x1a00
	v_mfma_f32_32x32x16_bf16 v[64:79], v[2:5], v[140:143], v[64:79]
	ds_read_b64_tr_b16 v[140:141], v14 offset:0x2200
	ds_read_b64_tr_b16 v[142:143], v14 offset:0x2a00
	v_mfma_f32_32x32x16_bf16 v[64:79], v[128:131], v[176:179], v[64:79]
	ds_read_b64_tr_b16 v[176:177], v14 offset:0x3200
	ds_read_b64_tr_b16 v[178:179], v14 offset:0x3a00
	s_waitcnt lgkmcnt(0)
	v_mfma_f32_32x32x16_bf16 v[64:79], v[10:13], v[180:183], v[64:79]
	v_mfma_f32_32x32x16_bf16 v[48:63], v[6:9], v[132:135], v[48:63]
	ds_read_b64_tr_b16 v[132:133], v14 offset:0x400
	ds_read_b64_tr_b16 v[134:135], v14 offset:0xc00
	v_mfma_f32_32x32x16_bf16 v[48:63], v[2:5], v[136:139], v[48:63]
	ds_read_b64_tr_b16 v[136:137], v14 offset:0x1400
	ds_read_b64_tr_b16 v[138:139], v14 offset:0x1c00
	v_mfma_f32_32x32x16_bf16 v[48:63], v[128:131], v[140:143], v[48:63]
	ds_read_b64_tr_b16 v[140:141], v14 offset:0x2400
	ds_read_b64_tr_b16 v[142:143], v14 offset:0x2c00
	v_mfma_f32_32x32x16_bf16 v[48:63], v[10:13], v[176:179], v[48:63]
	ds_read_b64_tr_b16 v[176:177], v14 offset:0x3400
	ds_read_b64_tr_b16 v[178:179], v14 offset:0x3c00
	s_waitcnt lgkmcnt(0)
	v_mfma_f32_32x32x16_bf16 v[32:47], v[6:9], v[132:135], v[32:47]
	ds_read_b64_tr_b16 v[132:133], v14 offset:0x600
	ds_read_b64_tr_b16 v[134:135], v14 offset:0xe00
	v_mfma_f32_32x32x16_bf16 v[32:47], v[2:5], v[136:139], v[32:47]
	ds_read_b64_tr_b16 v[136:137], v14 offset:0x1600
	ds_read_b64_tr_b16 v[138:139], v14 offset:0x1e00
	v_mfma_f32_32x32x16_bf16 v[32:47], v[128:131], v[140:143], v[32:47]
	ds_read_b64_tr_b16 v[140:141], v14 offset:0x2600
	ds_read_b64_tr_b16 v[142:143], v14 offset:0x2e00
	v_mfma_f32_32x32x16_bf16 v[32:47], v[10:13], v[176:179], v[32:47]
	ds_read_b64_tr_b16 v[176:177], v14 offset:0x3600
	ds_read_b64_tr_b16 v[178:179], v14 offset:0x3e00
	s_waitcnt lgkmcnt(0)
	s_cmpk_gt_u32 s17, 0xfb
	s_cbranch_scc1 .Lmy_slow_3
	s_mov_b64 s[14:15], -1
	s_add_i32 m0, s81, s26
	s_addk_i32 s31, 0xc000
	s_cmp_gt_i32 s18, 0
	s_cselect_b32 s14, s31, 0xc000
	s_waitcnt vmcnt(3) lgkmcnt(0)
	s_barrier
	v_mfma_f32_32x32x16_bf16 v[16:31], v[6:9], v[132:135], v[16:31]
	s_and_b64 vcc, exec, s[0:1]
	v_mfma_f32_32x32x16_bf16 v[16:31], v[2:5], v[136:139], v[16:31]
	v_mfma_f32_32x32x16_bf16 v[16:31], v[128:131], v[140:143], v[16:31]
	v_mfma_f32_32x32x16_bf16 v[16:31], v[10:13], v[176:179], v[16:31]
	s_add_i32 s14, s63, s14
	global_load_lds_dwordx4 v[184:185], off
	s_mov_b32 m0, s14
	v_lshl_add_u64 v[184:185], v[184:185], 0, s[74:75]
	global_load_lds_dwordx4 v[186:187], off
	s_add_i32 m0, s14, 0x2000
	v_lshl_add_u64 v[2:3], v[186:187], 0, s[74:75]
	global_load_lds_dwordx4 v[188:189], off
	v_lshl_add_u64 v[4:5], v[188:189], 0, s[74:75]
	v_mov_b64_e32 v[188:189], v[4:5]
	v_mov_b64_e32 v[186:187], v[2:3]
	s_branch .LBB0_799
